# E11 on E23: P0 XN prompt-row stores (dwordx2, 512B contiguous per wave) sc1
# speedup vs baseline: 1.0091x; 1.0074x over previous
.LBB0_96:
	s_andn2_b64 vcc, exec, s[0:1]
	s_cbranch_vccnz .LBB0_89
	global_load_dwordx4 v[26:29], v[14:15], off nt
	global_load_dwordx4 v[30:33], v[14:15], off offset:1024 nt
	global_load_dwordx4 v[34:37], v[14:15], off offset:3072 nt
	global_load_dwordx4 v[38:41], v[14:15], off offset:2048 nt
	s_waitcnt vmcnt(3)
	v_pk_mul_f32 v[42:43], v[28:29], v[28:29]
	v_pk_mul_f32 v[44:45], v[26:27], v[26:27]
	s_waitcnt vmcnt(2)
	v_pk_mul_f32 v[46:47], v[32:33], v[32:33]
	v_pk_mul_f32 v[48:49], v[30:31], v[30:31]
	v_pk_mov_b32 v[52:53], v[44:45], v[42:43] op_sel:[1,0]
	v_mov_b32_e32 v45, v43
	v_pk_mov_b32 v[42:43], v[48:49], v[46:47] op_sel:[1,0]
	v_mov_b32_e32 v49, v47
	s_waitcnt vmcnt(0)
	v_mul_f32_e32 v2, v39, v39
	v_mul_f32_e32 v50, v41, v41
	v_pk_add_f32 v[44:45], v[52:53], v[44:45]
	v_pk_add_f32 v[42:43], v[42:43], v[48:49]
	v_mul_f32_e32 v54, v34, v34
	v_mul_f32_e32 v55, v35, v35
	v_mul_f32_e32 v56, v36, v36
	v_mul_f32_e32 v57, v37, v37
	v_pk_fma_f32 v[46:47], v[38:39], v[38:39], v[2:3] op_sel_hi:[1,1,0]
	v_pk_fma_f32 v[50:51], v[40:41], v[40:41], v[50:51] op_sel_hi:[1,1,0]
	v_pk_add_f32 v[44:45], v[44:45], v[44:45] op_sel:[0,1] op_sel_hi:[1,0]
	v_pk_add_f32 v[42:43], v[42:43], v[42:43] op_sel:[0,1] op_sel_hi:[1,0]
	v_mov_b32_e32 v47, v56
	v_mov_b32_e32 v51, v57
	v_mov_b32_e32 v45, v54
	v_mov_b32_e32 v43, v55
	v_pk_add_f32 v[46:47], v[46:47], v[50:51]
	v_pk_add_f32 v[42:43], v[44:45], v[42:43]
	s_nop 0
	v_pk_add_f32 v[42:43], v[42:43], v[46:47]
	s_nop 0
	v_add_f32_e32 v2, v42, v43
	ds_bpermute_b32 v42, v16, v2
	s_waitcnt lgkmcnt(0)
	v_add_f32_e32 v2, v2, v42
	ds_bpermute_b32 v42, v17, v2
	s_waitcnt lgkmcnt(0)
	v_add_f32_e32 v2, v2, v42
	ds_bpermute_b32 v42, v18, v2
	s_waitcnt lgkmcnt(0)
	v_add_f32_e32 v2, v2, v42
	ds_bpermute_b32 v42, v19, v2
	s_waitcnt lgkmcnt(0)
	v_add_f32_e32 v2, v2, v42
	ds_bpermute_b32 v42, v20, v2
	s_waitcnt lgkmcnt(0)
	v_add_f32_e32 v2, v2, v42
	ds_bpermute_b32 v42, v21, v2
	s_waitcnt lgkmcnt(0)
	v_add_f32_e32 v2, v2, v42
	v_fmamk_f32 v2, v2, 0x3a800000, v24
	v_mul_f32_e32 v42, 0x4f800000, v2
	v_cmp_gt_f32_e32 vcc, s7, v2
	s_nop 1
	v_cndmask_b32_e32 v2, v2, v42, vcc
	v_sqrt_f32_e32 v42, v2
	s_nop 0
	v_add_u32_e32 v43, -1, v42
	v_add_u32_e32 v44, 1, v42
	v_fma_f32 v45, -v43, v42, v2
	v_fma_f32 v46, -v44, v42, v2
	v_cmp_ge_f32_e64 s[0:1], 0, v45
	s_nop 1
	v_cndmask_b32_e64 v42, v42, v43, s[0:1]
	v_cmp_lt_f32_e64 s[0:1], 0, v46
	s_nop 1
	v_cndmask_b32_e64 v42, v42, v44, s[0:1]
	v_mul_f32_e32 v43, 0x37800000, v42
	v_cndmask_b32_e32 v42, v42, v43, vcc
	v_cmp_class_f32_e32 vcc, v2, v25
	s_nop 1
	v_cndmask_b32_e32 v2, v42, v2, vcc
	v_div_scale_f32 v42, s[0:1], v2, v2, 1.0
	v_rcp_f32_e32 v43, v42
	v_div_scale_f32 v44, vcc, 1.0, v2, 1.0
	v_fma_f32 v45, -v42, v43, 1.0
	v_fmac_f32_e32 v43, v45, v43
	v_mul_f32_e32 v45, v44, v43
	v_fma_f32 v46, -v42, v45, v44
	v_fmac_f32_e32 v45, v46, v43
	v_fma_f32 v42, -v42, v45, v44
	v_div_fmas_f32 v42, v42, v43, v45
	v_div_fixup_f32 v2, v42, v2, 1.0
	v_pk_mul_f32 v[26:27], v[26:27], v[2:3] op_sel_hi:[1,0]
	v_pk_mul_f32 v[28:29], v[28:29], v[2:3] op_sel_hi:[1,0]
	v_pk_mul_f32 v[30:31], v[30:31], v[2:3] op_sel_hi:[1,0]
	v_pk_mul_f32 v[32:33], v[32:33], v[2:3] op_sel_hi:[1,0]
	v_pk_mul_f32 v[38:39], v[38:39], v[2:3] op_sel_hi:[1,0]
	v_pk_mul_f32 v[40:41], v[40:41], v[2:3] op_sel_hi:[1,0]
	v_pk_mul_f32 v[34:35], v[34:35], v[2:3] op_sel_hi:[1,0]
	v_pk_mul_f32 v[36:37], v[36:37], v[2:3] op_sel_hi:[1,0]
	v_cvt_pk_bf16_f32 v26, v26, v27
	v_cvt_pk_bf16_f32 v27, v28, v29
	v_cvt_pk_bf16_f32 v28, v30, v31
	v_cvt_pk_bf16_f32 v29, v32, v33
	v_cvt_pk_bf16_f32 v30, v38, v39
	v_cvt_pk_bf16_f32 v31, v40, v41
	v_cvt_pk_bf16_f32 v32, v34, v35
	v_cvt_pk_bf16_f32 v33, v36, v37
	global_store_dwordx2 v[12:13], v[26:27], off sc1
	global_store_dwordx2 v[12:13], v[28:29], off offset:512 sc1
	global_store_dwordx2 v[12:13], v[30:31], off offset:1024 sc1
	global_store_dwordx2 v[12:13], v[32:33], off offset:1536 sc1
	s_branch .LBB0_89
